# GEMM K-loop: per-MFMA-cluster s_setprio toggling removed; one static priority raise for the trailing wave half for the whole phase
# speedup vs baseline: 1.0039x; 1.0039x over previous
; __global__ void __launch_bounds__(NTHREADS, 2) mega_fwd(Params p) {
;     ...
;     for (int step = 0; step < 2 * SPL; ++step) {
;         const int l = step / SPL; int k = step % SPL; bool dry = false;
;         if (PROBE_STEP >= 0) { if (k == PROBE_STEP) dry = true; else if (k > PROBE_STEP) k -= 1; }
;         PPtr pp = (PPtr)__builtin_amdgcn_kernarg_segment_ptr(); asm volatile("" : "+s"(pp));
;         unsigned char* ws = pp->ws;
;         unsigned char* wb = ws + WS_W + (size_t)l * W_LAYER;
;         unsigned char* big = ws + WS_BIG;
;         bf16* HN = (bf16*)(ws + WS_HN);
;         float* xres = pp->out;
;         float* rssb = (float*)(ws + WS_RSP);
;         bool is_att = false, is_comb = false, sync_after = true;
;         const bf16* A = HN; const bf16* Bt = (const bf16*)wb; int N = D, K = D;
;         EpiAny E; E.pp = pp; E.lds = lds; E.kind = 1; E.layer = l; E.bi = 0; E.outf = nullptr; E.scale = 1.0f; E.rss_in = rssb; E.rss_out = rssb;
;         if (k == 0)       { A = HN; Bt = (const bf16*)(wb + W_1T); N = 2 * FF; K = D; E.kind = 0; E.rss_in = rssb; }
;         else if (k == 1)  { A = (const bf16*)big; Bt = (const bf16*)(wb + W_2T); N = D; K = FF; E.kind = 1; E.scale = 0.5f; }
;         else if (k == 2)  { A = HN; Bt = (const bf16*)(wb + W_INT); N = NQKV; K = D; E.kind = 2; E.rss_in = rssb; }
;         else if (k == 3)  { is_att = true; }
;         else if (k == 4)  { is_comb = true; }
;         else if (k < 13)  {
;             const int i = (k - 5) >> 1;
;             E.bi = i;
;             if (((k - 5) & 1) == 0) {
;                 const size_t aoff = (i == 0) ? B_QA : (i == 1 ? B_QB : (i == 2 ? B_QC : B_OD));
;                 const size_t woff = (i == 0) ? WB_A : (i == 1 ? WB_B : (i == 2 ? WB_C : WB_D));
;                 A = (const bf16*)(big + aoff); Bt = (const bf16*)(wb + W_BRT + woff); N = D; K = (i == 0) ? 512 : (i == 3 ? 256 : 384); E.kind = 3;
;             } else {
;                 A = HN; Bt = (const bf16*)(wb + W_GT) + (size_t)i * D * D; N = D; K = D; E.kind = 4; E.rss_in = rssb;
;             }
;             sync_after = (k == 12);
;         }
;         else if (k == 13) { A = (const bf16*)(big + B_MRG); Bt = (const bf16*)(wb + W_OT); N = D; K = D; E.kind = 1; E.scale = 1.0f; }
;         else if (k == 14) { A = HN; Bt = (const bf16*)(wb + W_3T); N = 2 * FF; K = D; E.kind = 0; E.rss_in = rssb; }
.LBB0_117:
	s_setprio 0
	v_readlane_b32 s42, v255, 2
	v_readlane_b32 s43, v255, 3
	s_load_dwordx4 s[24:27], s[42:43], 0xb0
	s_lshr_b32 s16, s74, 4
	s_and_b32 s1, s74, 15
	s_mul_i32 s3, s16, 0x3800000
	s_mul_hi_u32 s2, s16, 0x3800000
	s_waitcnt lgkmcnt(0)
	s_add_u32 s3, s26, s3
	s_addc_u32 s2, s27, s2
	s_add_u32 s6, s3, 0x200000
	s_addc_u32 s7, s2, 0
	s_add_u32 s2, s26, 0xb200000
	s_addc_u32 s3, s27, 0
	s_add_u32 s46, s26, 0x7200000
	v_writelane_b32 v255, s2, 23
	s_addc_u32 s47, s27, 0
	s_mov_b32 s17, s39
	v_writelane_b32 v255, s3, 24
	s_cmp_lt_i32 s1, 2
	s_mov_b64 s[8:9], -1
	s_cbranch_scc1 .LBB0_138
	s_cmp_lt_i32 s1, 3
	s_cbranch_scc1 .LBB0_148
	s_mov_b32 s14, 4
	s_cmp_lt_i32 s1, 4
	s_mov_b64 s[8:9], 0
	s_cbranch_scc1 .LBB0_146
	s_cmp_lg_u32 s1, 4
	s_mov_b64 s[12:13], -1
	s_cbranch_scc0 .LBB0_136
	s_mov_b64 s[78:79], -1
	s_cmp_gt_u32 s1, 12
	s_mov_b64 s[10:11], -1
	s_cbranch_scc0 .LBB0_130
	s_cmp_lt_i32 s1, 14
	s_mov_b64 s[4:5], -1
	s_cbranch_scc1 .LBB0_127
	s_cmp_lg_u32 s1, 14
	s_cbranch_scc0 .LBB0_125
	s_add_u32 s48, s6, 0x3280000
	s_addc_u32 s49, s7, 0
	s_cmp_eq_u32 s16, 1
	s_cselect_b32 s55, s25, 0
	s_cselect_b32 s54, s24, 0
	s_mov_b64 s[4:5], 0

; #define PG8_STAGE(bufoff, gbase, voff) do { _Pragma("unroll") for (int _i = 0; _i < 2; ++_i) \
;         __builtin_amdgcn_global_load_lds((const unsigned*)((const char*)(gbase) + (size_t)_i * r64 + (voff)), (PG8_LAS unsigned*)(lds + (bufoff) + ldsw + _i * 8192), 16, 0, 0); } while (0)
; #define PG8_WAIT_V(n) asm volatile("s_waitcnt vmcnt(" #n ")" ::: "memory")
; #define PG8_BAR __builtin_amdgcn_s_barrier()
; template <class Epi, class Sched, bool ALIGN_EPI = false, bool SP2 = false>
; __device__ __forceinline__ void gemm_phase(PG8_LAS unsigned char* lds, const Gemm g, const Sched& S, const Epi& E) {
;     ...
;     if constexpr (SP2) {
;         PG8_STAGE(PG8_SB(0, 0), cB, voffB); PG8_STAGE(PG8_SB(0, 1), cB + hstep, voffB); PG8_STAGE(PG8_SA(0, 0), cA, voffA); PG8_STAGE(PG8_SA(0, 1), cA + hstep, voffA);
;         if (wr == 1) PG8_BAR;
;         PG8_WAIT_V(2); PG8_BAR;
;         PG8_STAGE(PG8_SB(1, 0), cB + kstep, voffB); PG8_STAGE(PG8_SA(1, 0), cA + kstep, voffA); PG8_STAGE(PG8_SB(1, 1), cB + hstep + kstep, voffB);
;         PG8_WAIT_V(6); PG8_BAR;
;     } else {
;         PG8_STAGE(PG8_SB(0, 0), cB, voffB); PG8_STAGE(PG8_SA(0, 0), cA, voffA); PG8_STAGE(PG8_SB(0, 1), cB + hstep, voffB); PG8_STAGE(PG8_SA(0, 1), cA + hstep, voffA);
;         if (wr == 1) PG8_BAR;
;         PG8_WAIT_V(4); PG8_BAR;
;         PG8_STAGE(PG8_SB(1, 0), cB + kstep, voffB); PG8_STAGE(PG8_SA(1, 0), cA + kstep, voffA); PG8_STAGE(PG8_SB(1, 1), cB + hstep + kstep, voffB);
;         PG8_WAIT_V(6); PG8_BAR;
;     }
;     for (;;) {
;         const bool has_next = S.next(ui + 1, nxt);
;         const char* nA = has_next ? (const char*)g.A + (size_t)nxt.pm * tstep : cA; const char* nB = has_next ? (const char*)g.Bt + (size_t)nxt.pn * tstep : cB;
;         for (int t = 0; t < nt; t += 2) {
.LBB0_158:
	s_and_b32 s63, s2, 3
	s_lshr_b32 s2, s38, 6
	s_lshl_b32 s71, s1, 6
	s_lshl_b32 s5, s1, 13
	s_lshl_b32 s67, s63, 5
	s_lshl_b32 s7, s63, 12
	s_add_u32 s64, s26, 0x1fb00000
	s_addc_u32 s65, s27, 0
	v_lshl_add_u64 v[6:7], v[6:7], 0, s[34:35]
	s_add_i32 m0, s90, 0x18000
	s_waitcnt vmcnt(2)
	s_barrier
	global_load_lds_dwordx4 v[6:7], off
	v_lshl_add_u64 v[6:7], v[8:9], 0, s[34:35]
	s_add_i32 m0, s90, 0x1a000
	s_add_i32 s81, s90, 0x8000
	global_load_lds_dwordx4 v[6:7], off
	v_lshl_add_u64 v[6:7], v[12:13], 0, s[34:35]
	s_mov_b32 m0, s81
	s_add_i32 s1, s90, 0xa000
	global_load_lds_dwordx4 v[6:7], off
	v_lshl_add_u64 v[6:7], v[10:11], 0, s[34:35]
	s_mov_b32 m0, s1
	v_lshl_add_u64 v[2:3], v[2:3], 0, s[34:35]
	global_load_lds_dwordx4 v[6:7], off
	s_add_i32 m0, s90, 0x1c000
	s_add_i32 s70, s2, -2
	global_load_lds_dwordx4 v[2:3], off
	v_lshl_add_u64 v[2:3], v[4:5], 0, s[34:35]
	s_add_i32 m0, s90, 0x1e000
	v_bfe_u32 v241, v14, 4, 2
	global_load_lds_dwordx4 v[2:3], off
	s_cmpk_lt_u32 s3, 0x100
	v_and_b32_e32 v240, 15, v14
	v_lshlrev_b32_e32 v2, 4, v241
	v_lshlrev_b32_e32 v3, 2, v14
	s_cselect_b64 s[12:13], -1, 0
	s_lshl_b32 s3, s14, 4
	s_lshl_b32 s88, s14, 3
	v_lshl_or_b32 v2, v240, 6, v2
	v_and_b32_e32 v3, 32, v3
	v_writelane_b32 v255, s12, 34
	s_add_u32 s68, s26, 0x11200000
	v_bitop3_b32 v4, v2, s5, v3 bitop3:0xde
	v_bitop3_b32 v242, v2, s7, v3 bitop3:0xde
	v_writelane_b32 v255, s13, 35
	s_addc_u32 s69, s27, 0
	s_lshl_b32 s12, s16, 6
	v_cvt_f32_u32_e32 v2, s88
	s_add_u32 s20, s26, 0x100000
	v_writelane_b32 v255, s3, 36
	s_addc_u32 s21, s27, 0
	v_writelane_b32 v255, s20, 37
	s_cmp_eq_u64 s[54:55], 0
	v_rcp_iflag_f32_e32 v2, v2
	v_writelane_b32 v255, s21, 38
	s_mul_i32 s18, s16, 6
	s_cselect_b64 s[24:25], -1, 0
	s_cmp_lg_u64 s[54:55], 0
	v_writelane_b32 v255, s16, 39
	s_mov_b32 s5, s39
	s_cselect_b64 s[74:75], -1, 0
	v_writelane_b32 v255, s17, 40
	s_lshl_b32 s3, s16, 14
	s_lshl_b64 s[16:17], s[4:5], 12
	s_add_u32 s20, s26, 0x15200000
	s_addc_u32 s21, s27, 0
	v_mul_f32_e32 v2, 0x4f7ffffe, v2
	s_add_u32 s82, s26, 0x19200000
	v_cvt_u32_f32_e32 v2, v2
	s_addc_u32 s83, s27, 0
	s_cmp_lg_u32 s4, 0
	s_cselect_b64 s[84:85], -1, 0
	s_cmp_lg_u32 s4, 3
	v_writelane_b32 v255, s3, 41
	s_cselect_b64 s[86:87], -1, 0
	s_sub_i32 s3, 0, s88
	v_readfirstlane_b32 s4, v2
	s_mul_i32 s3, s3, s4
	v_add_u32_e32 v2, v17, v15
	v_writelane_b32 v255, s20, 42
	s_mul_hi_u32 s3, s4, s3
	v_add_lshl_u32 v2, v2, v16, 1
	v_mov_b32_e32 v3, v1
	s_mov_b32 s19, s39
	v_writelane_b32 v255, s21, 43
	s_add_i32 s3, s4, s3
	v_mad_u64_u32 v[220:221], s[4:5], s38, v235, v[2:3]
	v_writelane_b32 v255, s3, 44
	s_lshl_b64 s[4:5], s[18:19], 2
	s_mov_b32 s13, s39
	v_writelane_b32 v255, s4, 45
	s_waitcnt vmcnt(6)
	s_mov_b32 s7, s39
	s_mov_b32 s53, s52
	v_writelane_b32 v255, s5, 46
	s_lshl_b64 s[4:5], s[12:13], 2
	v_writelane_b32 v255, s4, 47
	s_mov_b32 s72, s52
	s_mov_b32 s73, s52
	s_mov_b32 s33, 0
	v_lshl_add_u64 v[218:219], s[58:59], 0, v[2:3]
	v_add_u32_e32 v243, 0, v4
	v_mov_b64_e32 v[222:223], s[6:7]
	v_writelane_b32 v255, s5, 48
	s_cmp_lt_u32 s41, 0x1000
	s_cbranch_scc1 .Lprio_lead
	s_setprio 1
.Lprio_lead:
	s_barrier
	s_branch .LBB0_161

; #define PG8_STAGE(bufoff, gbase, voff) do { _Pragma("unroll") for (int _i = 0; _i < 2; ++_i) \
;         __builtin_amdgcn_global_load_lds((const unsigned*)((const char*)(gbase) + (size_t)_i * r64 + (voff)), (PG8_LAS unsigned*)(lds + (bufoff) + ldsw + _i * 8192), 16, 0, 0); } while (0)
; #define PG8_LDA(dst, b, h) do { _Pragma("unroll") for (int m = 0; m < 4; ++m) _Pragma("unroll") for (int k = 0; k < 2; ++k) dst[m][k] = *(const PG8_LAS bf16x8*)(lds + PG8_SA(b, h) + aoff + m * 2048 + k * 1024); } while (0)
; #define PG8_LDB(dst, b, h) do { _Pragma("unroll") for (int n = 0; n < 2; ++n) _Pragma("unroll") for (int k = 0; k < 2; ++k) dst[n][k] = *(const PG8_LAS bf16x8*)(lds + PG8_SB(b, h) + boff + n * 2048 + k * 1024); } while (0)
; #define PG8_MMA(ai, bj, At, Bt) do { __builtin_amdgcn_s_setprio(1); _Pragma("unroll") for (int m = 0; m < 4; ++m) _Pragma("unroll") for (int n = 0; n < 2; ++n) _Pragma("unroll") for (int k = 0; k < 2; ++k) \
;         acc[ai][bj][m][n] = __builtin_amdgcn_mfma_f32_16x16x32_bf16(Bt[n][k], At[m][k], acc[ai][bj][m][n], 0, 0, 0); __builtin_amdgcn_s_setprio(0); } while (0)
; #define PG8_WAIT_V(n) asm volatile("s_waitcnt vmcnt(" #n ")" ::: "memory")
; #define PG8_WAIT_L(n) asm volatile("s_waitcnt lgkmcnt(" #n ")" ::: "memory")
; #define PG8_BAR __builtin_amdgcn_s_barrier()
; #define PG8_SCHED __builtin_amdgcn_sched_barrier(0)
; template <class Epi, class Sched, bool ALIGN_EPI = false, bool SP2 = false>
; __device__ __forceinline__ void gemm_phase(PG8_LAS unsigned char* lds, const Gemm g, const Sched& S, const Epi& E) {
;     ...
;             PG8_LDB(B0, 0, 0); PG8_LDB(B1, 0, 1); PG8_SCHED; PG8_LDA(At, 0, 0); PG8_STAGE(PG8_SA(1, 1), a1 + hstep, voffA);
;             PG8_WAIT_V(8); PG8_WAIT_L(0); PG8_BAR; PG8_MMA(0, 0, At, B0); PG8_MMA(0, 1, At, B1); PG8_BAR; PG8_SCHED;
;             PG8_LDA(At, 0, 1); PG8_STAGE(PG8_SB(0, 0), b2, voffB); PG8_STAGE(PG8_SB(0, 1), b2 + hstep, voffB); PG8_STAGE(PG8_SA(0, 0), a2, voffA);
;             PG8_WAIT_V(8); PG8_WAIT_L(0); PG8_BAR; PG8_MMA(1, 0, At, B0); PG8_MMA(1, 1, At, B1); PG8_BAR; PG8_SCHED;
.LBB0_167:
	v_and_b32_e32 v2, 63, v214
	s_lshl_b32 s12, s45, 14
	s_lshl_b32 s3, s41, 1
	v_lshlrev_b32_e32 v2, 4, v2
	s_add_u32 s12, s12, s3
	s_add_u32 s12, s64, s12
	s_addc_u32 s13, s65, 0
	s_add_i32 m0, s3, 0x21000
	s_nop 0
	global_load_lds_dwordx4 v2, s[12:13]
	global_load_lds_dwordx4 v2, s[12:13] offset:1024
	s_add_u32 s6, s10, 0x80
	s_addc_u32 s7, s11, 0
	s_add_u32 s10, s8, 0x100
	s_addc_u32 s11, s9, 0
	s_mov_b32 s8, 0
	s_add_i32 s12, s8, 2
	s_add_u32 s3, s6, 0x80
	s_addc_u32 s9, s7, 0
	s_add_i32 s13, 0, 0x10000
	s_cmp_eq_u32 s70, s8
	s_cselect_b32 s9, s93, s9
	s_cselect_b32 s8, s92, s3
	s_cselect_b32 s19, s95, s11
	s_cselect_b32 s18, s94, s10
	s_add_i32 s3, 0, 0x14000
	v_add_u32_e32 v14, s13, v242
	v_add_u32_e32 v30, s3, v242
	s_waitcnt lgkmcnt(0)
	ds_read_b128 v[2:5], v14
	ds_read_b128 v[6:9], v14 offset:1024
	ds_read_b128 v[10:13], v14 offset:2048
	ds_read_b128 v[14:17], v14 offset:3072
	ds_read_b128 v[18:21], v30
	ds_read_b128 v[22:25], v30 offset:1024
	ds_read_b128 v[26:29], v30 offset:2048
	ds_read_b128 v[30:33], v30 offset:3072
	v_lshl_add_u64 v[194:195], s[6:7], 0, v[218:219]
	s_add_i32 m0, s90, 0xc000
	ds_read_b128 v[34:37], v243
	ds_read_b128 v[38:41], v243 offset:1024
	ds_read_b128 v[42:45], v243 offset:2048
	ds_read_b128 v[46:49], v243 offset:3072
	ds_read_b128 v[50:53], v243 offset:4096
	ds_read_b128 v[54:57], v243 offset:5120
	ds_read_b128 v[58:61], v243 offset:6144
	ds_read_b128 v[62:65], v243 offset:7168
	global_load_lds_dwordx4 v[194:195], off
	v_lshl_add_u64 v[194:195], s[6:7], 0, v[220:221]
	s_add_i32 m0, s90, 0xe000
	s_nop 0
	global_load_lds_dwordx4 v[194:195], off
	s_waitcnt vmcnt(8)
	s_waitcnt lgkmcnt(0)
	s_barrier
	s_waitcnt lgkmcnt(0)
	v_mfma_f32_16x16x32_bf16 v[190:193], v[2:5], v[34:37], 0
	v_mfma_f32_16x16x32_bf16 v[186:189], v[10:13], v[34:37], 0
	v_mfma_f32_16x16x32_bf16 v[174:177], v[2:5], v[42:45], 0
	v_mfma_f32_16x16x32_bf16 v[170:173], v[10:13], v[42:45], 0
	v_mfma_f32_16x16x32_bf16 v[158:161], v[2:5], v[50:53], 0
	v_mfma_f32_16x16x32_bf16 v[154:157], v[10:13], v[50:53], 0
	v_mfma_f32_16x16x32_bf16 v[142:145], v[2:5], v[58:61], 0
	v_mfma_f32_16x16x32_bf16 v[138:141], v[10:13], v[58:61], 0
	v_mfma_f32_16x16x32_bf16 v[190:193], v[6:9], v[38:41], v[190:193]
	v_mfma_f32_16x16x32_bf16 v[186:189], v[14:17], v[38:41], v[186:189]
	v_mfma_f32_16x16x32_bf16 v[174:177], v[6:9], v[46:49], v[174:177]
	v_mfma_f32_16x16x32_bf16 v[170:173], v[14:17], v[46:49], v[170:173]
	v_mfma_f32_16x16x32_bf16 v[158:161], v[6:9], v[54:57], v[158:161]
	v_mfma_f32_16x16x32_bf16 v[154:157], v[14:17], v[54:57], v[154:157]
	v_mfma_f32_16x16x32_bf16 v[142:145], v[6:9], v[62:65], v[142:145]
	v_mfma_f32_16x16x32_bf16 v[138:141], v[14:17], v[62:65], v[138:141]
	v_mfma_f32_16x16x32_bf16 v[182:185], v[18:21], v[34:37], 0
	v_mfma_f32_16x16x32_bf16 v[34:37], v[26:29], v[34:37], 0
	v_mfma_f32_16x16x32_bf16 v[182:185], v[22:25], v[38:41], v[182:185]
	v_mfma_f32_16x16x32_bf16 v[34:37], v[30:33], v[38:41], v[34:37]
	v_mfma_f32_16x16x32_bf16 v[38:41], v[18:21], v[42:45], 0
	v_mfma_f32_16x16x32_bf16 v[42:45], v[26:29], v[42:45], 0
	v_mfma_f32_16x16x32_bf16 v[38:41], v[22:25], v[46:49], v[38:41]
	v_mfma_f32_16x16x32_bf16 v[42:45], v[30:33], v[46:49], v[42:45]
	v_mfma_f32_16x16x32_bf16 v[46:49], v[18:21], v[50:53], 0
	v_mfma_f32_16x16x32_bf16 v[50:53], v[26:29], v[50:53], 0
	v_mfma_f32_16x16x32_bf16 v[46:49], v[22:25], v[54:57], v[46:49]
	v_mfma_f32_16x16x32_bf16 v[50:53], v[30:33], v[54:57], v[50:53]
	v_mfma_f32_16x16x32_bf16 v[54:57], v[18:21], v[58:61], 0
	v_mfma_f32_16x16x32_bf16 v[58:61], v[26:29], v[58:61], 0
	v_mfma_f32_16x16x32_bf16 v[54:57], v[22:25], v[62:65], v[54:57]
	v_mfma_f32_16x16x32_bf16 v[58:61], v[30:33], v[62:65], v[58:61]
	s_barrier
	s_add_i32 s13, s13, s41
	v_lshl_add_u64 v[228:229], s[18:19], 0, v[0:1]
	s_mov_b32 m0, s13
	ds_read_b128 v[62:65], v243 offset:16384
	ds_read_b128 v[130:133], v243 offset:17408
	ds_read_b128 v[134:137], v243 offset:18432
	ds_read_b128 v[146:149], v243 offset:19456
	ds_read_b128 v[150:153], v243 offset:20480
	ds_read_b128 v[162:165], v243 offset:21504
	ds_read_b128 v[166:169], v243 offset:22528
	ds_read_b128 v[178:181], v243 offset:23552
	global_load_lds_dwordx4 v[228:229], off
	s_add_i32 m0, s13, 0x2000
	s_add_u32 s18, s18, s58
	v_lshl_add_u64 v[230:231], v[228:229], 0, s[56:57]
	s_addc_u32 s19, s19, s59
	s_add_i32 s3, s3, s41
	global_load_lds_dwordx4 v[230:231], off
	v_lshl_add_u64 v[244:245], s[18:19], 0, v[0:1]
	s_mov_b32 m0, s3
	v_lshl_add_u64 v[246:247], v[244:245], 0, s[56:57]
	global_load_lds_dwordx4 v[244:245], off
	s_add_i32 m0, s3, 0x2000
	v_lshl_add_u64 v[248:249], s[8:9], 0, v[216:217]
	global_load_lds_dwordx4 v[246:247], off
	s_mov_b32 m0, s90
	v_lshl_add_u64 v[250:251], v[248:249], 0, s[56:57]
	global_load_lds_dwordx4 v[248:249], off
	s_mov_b32 m0, s91
	s_nop 0
	global_load_lds_dwordx4 v[250:251], off
	s_waitcnt vmcnt(8)
	s_waitcnt lgkmcnt(0)
	s_barrier
; #define PG8_STAGE(bufoff, gbase, voff) do { _Pragma("unroll") for (int _i = 0; _i < 2; ++_i) \
;         __builtin_amdgcn_global_load_lds((const unsigned*)((const char*)(gbase) + (size_t)_i * r64 + (voff)), (PG8_LAS unsigned*)(lds + (bufoff) + ldsw + _i * 8192), 16, 0, 0); } while (0)
; #define PG8_LDA(dst, b, h) do { _Pragma("unroll") for (int m = 0; m < 4; ++m) _Pragma("unroll") for (int k = 0; k < 2; ++k) dst[m][k] = *(const PG8_LAS bf16x8*)(lds + PG8_SA(b, h) + aoff + m * 2048 + k * 1024); } while (0)
; #define PG8_LDB(dst, b, h) do { _Pragma("unroll") for (int n = 0; n < 2; ++n) _Pragma("unroll") for (int k = 0; k < 2; ++k) dst[n][k] = *(const PG8_LAS bf16x8*)(lds + PG8_SB(b, h) + boff + n * 2048 + k * 1024); } while (0)
; #define PG8_MMA(ai, bj, At, Bt) do { __builtin_amdgcn_s_setprio(1); _Pragma("unroll") for (int m = 0; m < 4; ++m) _Pragma("unroll") for (int n = 0; n < 2; ++n) _Pragma("unroll") for (int k = 0; k < 2; ++k) \
;         acc[ai][bj][m][n] = __builtin_amdgcn_mfma_f32_16x16x32_bf16(Bt[n][k], At[m][k], acc[ai][bj][m][n], 0, 0, 0); __builtin_amdgcn_s_setprio(0); } while (0)
; #define PG8_WAIT_V(n) asm volatile("s_waitcnt vmcnt(" #n ")" ::: "memory")
; #define PG8_WAIT_L(n) asm volatile("s_waitcnt lgkmcnt(" #n ")" ::: "memory")
; #define PG8_BAR __builtin_amdgcn_s_barrier()
; #define PG8_SCHED __builtin_amdgcn_sched_barrier(0)
; template <class Epi, class Sched, bool ALIGN_EPI = false, bool SP2 = false>
; __device__ __forceinline__ void gemm_phase(PG8_LAS unsigned char* lds, const Gemm g, const Sched& S, const Epi& E) {
;     ...
;             PG8_WAIT_V(8); PG8_WAIT_L(0); PG8_BAR; PG8_MMA(1, 0, At, B0); PG8_MMA(1, 1, At, B1); PG8_BAR; PG8_SCHED;
;             PG8_LDB(B0, 1, 0); PG8_LDB(B1, 1, 1); PG8_SCHED; PG8_LDA(At, 1, 0); PG8_STAGE(PG8_SA(0, 1), a2 + hstep, voffA);
;             PG8_WAIT_V(8); PG8_WAIT_L(0); PG8_BAR; PG8_MMA(0, 0, At, B0); PG8_MMA(0, 1, At, B1); PG8_BAR; PG8_SCHED;
	s_waitcnt lgkmcnt(0)
	v_mfma_f32_16x16x32_bf16 v[126:129], v[2:5], v[62:65], 0
	v_mfma_f32_16x16x32_bf16 v[122:125], v[10:13], v[62:65], 0
	v_mfma_f32_16x16x32_bf16 v[110:113], v[2:5], v[134:137], 0
	v_mfma_f32_16x16x32_bf16 v[106:109], v[10:13], v[134:137], 0
	v_mfma_f32_16x16x32_bf16 v[94:97], v[2:5], v[150:153], 0
	v_mfma_f32_16x16x32_bf16 v[90:93], v[10:13], v[150:153], 0
	v_mfma_f32_16x16x32_bf16 v[2:5], v[2:5], v[166:169], 0
	v_mfma_f32_16x16x32_bf16 v[126:129], v[6:9], v[130:133], v[126:129]
	v_mfma_f32_16x16x32_bf16 v[122:125], v[14:17], v[130:133], v[122:125]
	v_mfma_f32_16x16x32_bf16 v[110:113], v[6:9], v[146:149], v[110:113]
	v_mfma_f32_16x16x32_bf16 v[106:109], v[14:17], v[146:149], v[106:109]
	v_mfma_f32_16x16x32_bf16 v[94:97], v[6:9], v[162:165], v[94:97]
	v_mfma_f32_16x16x32_bf16 v[90:93], v[14:17], v[162:165], v[90:93]
	v_mfma_f32_16x16x32_bf16 v[2:5], v[6:9], v[178:181], v[2:5]
	v_mfma_f32_16x16x32_bf16 v[6:9], v[10:13], v[166:169], 0
	v_mfma_f32_16x16x32_bf16 v[6:9], v[14:17], v[178:181], v[6:9]
	v_mfma_f32_16x16x32_bf16 v[74:77], v[26:29], v[134:137], 0
	v_mfma_f32_16x16x32_bf16 v[98:101], v[30:33], v[146:149], v[74:77]
	v_mfma_f32_16x16x32_bf16 v[74:77], v[18:21], v[150:153], 0
	v_mfma_f32_16x16x32_bf16 v[10:13], v[18:21], v[62:65], 0
	v_mfma_f32_16x16x32_bf16 v[14:17], v[26:29], v[62:65], 0
	v_mfma_f32_16x16x32_bf16 v[62:65], v[18:21], v[134:137], 0
	v_mfma_f32_16x16x32_bf16 v[86:89], v[22:25], v[162:165], v[74:77]
	v_mfma_f32_16x16x32_bf16 v[74:77], v[26:29], v[150:153], 0
	v_mfma_f32_16x16x32_bf16 v[18:21], v[18:21], v[166:169], 0
	v_mfma_f32_16x16x32_bf16 v[10:13], v[22:25], v[130:133], v[10:13]
	v_mfma_f32_16x16x32_bf16 v[62:65], v[22:25], v[146:149], v[62:65]
	v_mfma_f32_16x16x32_bf16 v[82:85], v[30:33], v[162:165], v[74:77]
	v_mfma_f32_16x16x32_bf16 v[18:21], v[22:25], v[178:181], v[18:21]
	v_mfma_f32_16x16x32_bf16 v[22:25], v[26:29], v[166:169], 0
	v_mfma_f32_16x16x32_bf16 v[14:17], v[30:33], v[130:133], v[14:17]
	v_mfma_f32_16x16x32_bf16 v[22:25], v[30:33], v[178:181], v[22:25]
	s_barrier
	s_add_i32 s3, 0, 0x18000
	s_add_i32 s13, 0, 0x1c000
	v_add_u32_e32 v70, s3, v242
	v_add_u32_e32 v74, s13, v242
	ds_read_b128 v[26:29], v70
	ds_read_b128 v[30:33], v70 offset:1024
	ds_read_b128 v[66:69], v70 offset:2048
	ds_read_b128 v[70:73], v70 offset:3072
	ds_read_b128 v[194:197], v74
	ds_read_b128 v[198:201], v74 offset:1024
	ds_read_b128 v[202:205], v74 offset:2048
	ds_read_b128 v[206:209], v74 offset:3072
	s_add_u32 s8, s8, s58
	s_addc_u32 s9, s9, s59
	s_mov_b32 m0, s36
	v_lshl_add_u64 v[134:135], s[8:9], 0, v[216:217]
	ds_read_b128 v[74:77], v243 offset:32768
	ds_read_b128 v[78:81], v243 offset:33792
	ds_read_b128 v[102:105], v243 offset:34816
	ds_read_b128 v[114:117], v243 offset:35840
	ds_read_b128 v[118:121], v243 offset:36864
	ds_read_b128 v[130:133], v243 offset:37888
	ds_read_b128 v[210:213], v243 offset:38912
	ds_read_b128 v[224:227], v243 offset:39936
	global_load_lds_dwordx4 v[134:135], off
	v_lshl_add_u64 v[134:135], v[134:135], 0, s[56:57]
	s_mov_b32 m0, s62
	s_nop 0
	global_load_lds_dwordx4 v[134:135], off
	s_waitcnt vmcnt(8)
	s_waitcnt lgkmcnt(0)
	s_barrier
	s_waitcnt lgkmcnt(0)
	v_mfma_f32_16x16x32_bf16 v[134:137], v[26:29], v[74:77], v[190:193]
	v_mfma_f32_16x16x32_bf16 v[190:193], v[30:33], v[78:81], v[134:137]
	v_mfma_f32_16x16x32_bf16 v[134:137], v[66:69], v[74:77], v[186:189]
	v_mfma_f32_16x16x32_bf16 v[186:189], v[70:73], v[78:81], v[134:137]
	v_mfma_f32_16x16x32_bf16 v[134:137], v[26:29], v[102:105], v[174:177]
	v_mfma_f32_16x16x32_bf16 v[174:177], v[30:33], v[114:117], v[134:137]
	v_mfma_f32_16x16x32_bf16 v[134:137], v[66:69], v[102:105], v[170:173]
	v_mfma_f32_16x16x32_bf16 v[170:173], v[70:73], v[114:117], v[134:137]
	v_mfma_f32_16x16x32_bf16 v[134:137], v[26:29], v[118:121], v[158:161]
	v_mfma_f32_16x16x32_bf16 v[158:161], v[30:33], v[130:133], v[134:137]
	v_mfma_f32_16x16x32_bf16 v[134:137], v[66:69], v[118:121], v[154:157]
	v_mfma_f32_16x16x32_bf16 v[154:157], v[70:73], v[130:133], v[134:137]
	v_mfma_f32_16x16x32_bf16 v[134:137], v[26:29], v[210:213], v[142:145]
	v_mfma_f32_16x16x32_bf16 v[142:145], v[30:33], v[224:227], v[134:137]
	v_mfma_f32_16x16x32_bf16 v[134:137], v[66:69], v[210:213], v[138:141]
	v_mfma_f32_16x16x32_bf16 v[138:141], v[70:73], v[224:227], v[134:137]
	v_mfma_f32_16x16x32_bf16 v[34:37], v[202:205], v[74:77], v[34:37]
	v_mfma_f32_16x16x32_bf16 v[178:181], v[206:209], v[78:81], v[34:37]
	v_mfma_f32_16x16x32_bf16 v[34:37], v[194:197], v[102:105], v[38:41]
	v_mfma_f32_16x16x32_bf16 v[166:169], v[198:201], v[114:117], v[34:37]
	v_mfma_f32_16x16x32_bf16 v[34:37], v[202:205], v[102:105], v[42:45]
	v_mfma_f32_16x16x32_bf16 v[162:165], v[206:209], v[114:117], v[34:37]
	v_mfma_f32_16x16x32_bf16 v[34:37], v[194:197], v[118:121], v[46:49]
	v_mfma_f32_16x16x32_bf16 v[150:153], v[198:201], v[130:133], v[34:37]
	v_mfma_f32_16x16x32_bf16 v[34:37], v[202:205], v[118:121], v[50:53]
	v_mfma_f32_16x16x32_bf16 v[134:137], v[194:197], v[74:77], v[182:185]
	v_mfma_f32_16x16x32_bf16 v[146:149], v[206:209], v[130:133], v[34:37]
	v_mfma_f32_16x16x32_bf16 v[34:37], v[194:197], v[210:213], v[54:57]
	v_mfma_f32_16x16x32_bf16 v[182:185], v[198:201], v[78:81], v[134:137]
	v_mfma_f32_16x16x32_bf16 v[134:137], v[198:201], v[224:227], v[34:37]
	v_mfma_f32_16x16x32_bf16 v[34:37], v[202:205], v[210:213], v[58:61]
	v_mfma_f32_16x16x32_bf16 v[130:133], v[206:209], v[224:227], v[34:37]
	s_barrier
; #define PG8_STAGE(bufoff, gbase, voff) do { _Pragma("unroll") for (int _i = 0; _i < 2; ++_i) \
;         __builtin_amdgcn_global_load_lds((const unsigned*)((const char*)(gbase) + (size_t)_i * r64 + (voff)), (PG8_LAS unsigned*)(lds + (bufoff) + ldsw + _i * 8192), 16, 0, 0); } while (0)
; #define PG8_LDA(dst, b, h) do { _Pragma("unroll") for (int m = 0; m < 4; ++m) _Pragma("unroll") for (int k = 0; k < 2; ++k) dst[m][k] = *(const PG8_LAS bf16x8*)(lds + PG8_SA(b, h) + aoff + m * 2048 + k * 1024); } while (0)
; #define PG8_LDB(dst, b, h) do { _Pragma("unroll") for (int n = 0; n < 2; ++n) _Pragma("unroll") for (int k = 0; k < 2; ++k) dst[n][k] = *(const PG8_LAS bf16x8*)(lds + PG8_SB(b, h) + boff + n * 2048 + k * 1024); } while (0)
; #define PG8_MMA(ai, bj, At, Bt) do { __builtin_amdgcn_s_setprio(1); _Pragma("unroll") for (int m = 0; m < 4; ++m) _Pragma("unroll") for (int n = 0; n < 2; ++n) _Pragma("unroll") for (int k = 0; k < 2; ++k) \
;         acc[ai][bj][m][n] = __builtin_amdgcn_mfma_f32_16x16x32_bf16(Bt[n][k], At[m][k], acc[ai][bj][m][n], 0, 0, 0); __builtin_amdgcn_s_setprio(0); } while (0)
; #define PG8_WAIT_V(n) asm volatile("s_waitcnt vmcnt(" #n ")" ::: "memory")
; #define PG8_WAIT_L(n) asm volatile("s_waitcnt lgkmcnt(" #n ")" ::: "memory")
; #define PG8_BAR __builtin_amdgcn_s_barrier()
; #define PG8_SCHED __builtin_amdgcn_sched_barrier(0)
; template <class Epi, class Sched, bool ALIGN_EPI = false, bool SP2 = false>
; __device__ __forceinline__ void gemm_phase(PG8_LAS unsigned char* lds, const Gemm g, const Sched& S, const Epi& E) {
;     ...
;             PG8_LDB(B0, 0, 0); PG8_LDB(B1, 0, 1); PG8_SCHED; PG8_LDA(At, 0, 0); PG8_STAGE(PG8_SA(1, 1), a1 + hstep, voffA);
;             PG8_WAIT_V(8); PG8_WAIT_L(0); PG8_BAR; PG8_MMA(0, 0, At, B0); PG8_MMA(0, 1, At, B1); PG8_BAR; PG8_SCHED;
;             PG8_LDA(At, 0, 1); PG8_STAGE(PG8_SB(0, 0), b2, voffB); PG8_STAGE(PG8_SB(0, 1), b2 + hstep, voffB); PG8_STAGE(PG8_SA(0, 0), a2, voffA);
;     ...
;             PG8_WAIT_V(8); PG8_WAIT_L(0); PG8_BAR; PG8_MMA(0, 0, At, B0); PG8_MMA(0, 1, At, B1); PG8_BAR; PG8_SCHED;
;             PG8_LDA(At, 1, 1); PG8_STAGE(PG8_SB(1, 0), b3, voffB); PG8_STAGE(PG8_SB(1, 1), b3 + hstep, voffB); PG8_STAGE(PG8_SA(1, 0), a3, voffA);
;             PG8_WAIT_V(8); PG8_WAIT_L(0); PG8_BAR; PG8_MMA(1, 0, At, B0); PG8_MMA(1, 1, At, B1); PG8_BAR; PG8_SCHED;
	s_add_i32 s3, s3, s41
	v_lshl_add_u64 v[74:75], v[228:229], 0, s[34:35]
	s_mov_b32 m0, s3
	s_nop 1
	ds_read_b128 v[34:37], v243 offset:49152
	ds_read_b128 v[38:41], v243 offset:50176
	ds_read_b128 v[42:45], v243 offset:51200
	ds_read_b128 v[46:49], v243 offset:52224
	ds_read_b128 v[50:53], v243 offset:53248
	ds_read_b128 v[54:57], v243 offset:54272
	ds_read_b128 v[58:61], v243 offset:55296
	ds_read_b128 v[210:213], v243 offset:56320
	global_load_lds_dwordx4 v[74:75], off
	v_lshl_add_u64 v[74:75], v[230:231], 0, s[34:35]
	s_add_i32 m0, s3, 0x2000
	s_add_i32 s3, s13, s41
	global_load_lds_dwordx4 v[74:75], off
	v_lshl_add_u64 v[74:75], v[244:245], 0, s[34:35]
	s_mov_b32 m0, s3
	s_nop 0
	global_load_lds_dwordx4 v[74:75], off
	v_lshl_add_u64 v[74:75], v[246:247], 0, s[34:35]
	s_add_i32 m0, s3, 0x2000
	s_nop 0
	global_load_lds_dwordx4 v[74:75], off
	v_lshl_add_u64 v[74:75], v[248:249], 0, s[34:35]
	s_mov_b32 m0, s81
	s_nop 0
	global_load_lds_dwordx4 v[74:75], off
	v_lshl_add_u64 v[74:75], v[250:251], 0, s[34:35]
	s_mov_b32 m0, s1
	s_nop 0
	global_load_lds_dwordx4 v[74:75], off
	s_waitcnt vmcnt(8)
	s_waitcnt lgkmcnt(0)
	s_barrier
	s_waitcnt lgkmcnt(0)
	v_mfma_f32_16x16x32_bf16 v[74:77], v[26:29], v[34:37], v[126:129]
	v_mfma_f32_16x16x32_bf16 v[126:129], v[30:33], v[38:41], v[74:77]
	v_mfma_f32_16x16x32_bf16 v[74:77], v[66:69], v[34:37], v[122:125]
	v_mfma_f32_16x16x32_bf16 v[122:125], v[70:73], v[38:41], v[74:77]
	v_mfma_f32_16x16x32_bf16 v[74:77], v[26:29], v[42:45], v[110:113]
	v_mfma_f32_16x16x32_bf16 v[110:113], v[30:33], v[46:49], v[74:77]
	v_mfma_f32_16x16x32_bf16 v[74:77], v[66:69], v[42:45], v[106:109]
	v_mfma_f32_16x16x32_bf16 v[106:109], v[70:73], v[46:49], v[74:77]
	v_mfma_f32_16x16x32_bf16 v[74:77], v[26:29], v[50:53], v[94:97]
	v_mfma_f32_16x16x32_bf16 v[2:5], v[26:29], v[58:61], v[2:5]
	v_mfma_f32_16x16x32_bf16 v[94:97], v[30:33], v[54:57], v[74:77]
	v_mfma_f32_16x16x32_bf16 v[74:77], v[66:69], v[50:53], v[90:93]
	v_mfma_f32_16x16x32_bf16 v[78:81], v[30:33], v[210:213], v[2:5]
	v_mfma_f32_16x16x32_bf16 v[2:5], v[66:69], v[58:61], v[6:9]
	v_mfma_f32_16x16x32_bf16 v[90:93], v[70:73], v[54:57], v[74:77]
	v_mfma_f32_16x16x32_bf16 v[74:77], v[70:73], v[210:213], v[2:5]
	v_mfma_f32_16x16x32_bf16 v[2:5], v[194:197], v[34:37], v[10:13]
	v_mfma_f32_16x16x32_bf16 v[118:121], v[198:201], v[38:41], v[2:5]
	v_mfma_f32_16x16x32_bf16 v[2:5], v[202:205], v[34:37], v[14:17]
	v_mfma_f32_16x16x32_bf16 v[114:117], v[206:209], v[38:41], v[2:5]
	v_mfma_f32_16x16x32_bf16 v[2:5], v[194:197], v[42:45], v[62:65]
	v_mfma_f32_16x16x32_bf16 v[102:105], v[198:201], v[46:49], v[2:5]
	v_mfma_f32_16x16x32_bf16 v[2:5], v[202:205], v[42:45], v[98:101]
	v_mfma_f32_16x16x32_bf16 v[98:101], v[206:209], v[46:49], v[2:5]
	v_mfma_f32_16x16x32_bf16 v[2:5], v[194:197], v[50:53], v[86:89]
	v_mfma_f32_16x16x32_bf16 v[86:89], v[198:201], v[54:57], v[2:5]
	v_mfma_f32_16x16x32_bf16 v[2:5], v[202:205], v[50:53], v[82:85]
	v_mfma_f32_16x16x32_bf16 v[82:85], v[206:209], v[54:57], v[2:5]
	v_mfma_f32_16x16x32_bf16 v[2:5], v[194:197], v[58:61], v[18:21]
	v_mfma_f32_16x16x32_bf16 v[70:73], v[198:201], v[210:213], v[2:5]
	v_mfma_f32_16x16x32_bf16 v[2:5], v[202:205], v[58:61], v[22:25]
	v_mfma_f32_16x16x32_bf16 v[66:69], v[206:209], v[210:213], v[2:5]
	s_barrier
	s_add_u32 s6, s6, 0x100
	s_addc_u32 s7, s7, 0
	s_add_u32 s10, s10, 0x100
	s_addc_u32 s11, s11, 0
	s_cmp_ge_u32 s12, s2
	s_mov_b32 s8, s12
	s_cbranch_scc1 .Lkloop_done
.LBB0_168:
	s_add_i32 s12, s8, 2
	s_add_u32 s3, s6, 0x80
	s_addc_u32 s9, s7, 0
	s_add_i32 s13, 0, 0x10000
	s_cmp_eq_u32 s70, s8
	s_cselect_b32 s9, s93, s9
	s_cselect_b32 s8, s92, s3
	s_cselect_b32 s19, s95, s11
	s_cselect_b32 s18, s94, s10
	s_add_i32 s3, 0, 0x14000
	v_add_u32_e32 v14, s13, v242
	v_add_u32_e32 v30, s3, v242
	s_waitcnt lgkmcnt(0)
	ds_read_b128 v[2:5], v14
	ds_read_b128 v[6:9], v14 offset:1024
	ds_read_b128 v[10:13], v14 offset:2048
	ds_read_b128 v[14:17], v14 offset:3072
	ds_read_b128 v[18:21], v30
	ds_read_b128 v[22:25], v30 offset:1024
	ds_read_b128 v[26:29], v30 offset:2048
	ds_read_b128 v[30:33], v30 offset:3072
	v_lshl_add_u64 v[194:195], s[6:7], 0, v[218:219]
	s_add_i32 m0, s90, 0xc000
	ds_read_b128 v[34:37], v243
	ds_read_b128 v[38:41], v243 offset:1024
	ds_read_b128 v[42:45], v243 offset:2048
	ds_read_b128 v[46:49], v243 offset:3072
	ds_read_b128 v[50:53], v243 offset:4096
	ds_read_b128 v[54:57], v243 offset:5120
	ds_read_b128 v[58:61], v243 offset:6144
	ds_read_b128 v[62:65], v243 offset:7168
	global_load_lds_dwordx4 v[194:195], off
	v_lshl_add_u64 v[194:195], s[6:7], 0, v[220:221]
	s_add_i32 m0, s90, 0xe000
	s_nop 0
	global_load_lds_dwordx4 v[194:195], off
	s_waitcnt vmcnt(8)
	s_waitcnt lgkmcnt(0)
	s_barrier
; #define PG8_STAGE(bufoff, gbase, voff) do { _Pragma("unroll") for (int _i = 0; _i < 2; ++_i) \
;         __builtin_amdgcn_global_load_lds((const unsigned*)((const char*)(gbase) + (size_t)_i * r64 + (voff)), (PG8_LAS unsigned*)(lds + (bufoff) + ldsw + _i * 8192), 16, 0, 0); } while (0)
; #define PG8_LDA(dst, b, h) do { _Pragma("unroll") for (int m = 0; m < 4; ++m) _Pragma("unroll") for (int k = 0; k < 2; ++k) dst[m][k] = *(const PG8_LAS bf16x8*)(lds + PG8_SA(b, h) + aoff + m * 2048 + k * 1024); } while (0)
; #define PG8_LDB(dst, b, h) do { _Pragma("unroll") for (int n = 0; n < 2; ++n) _Pragma("unroll") for (int k = 0; k < 2; ++k) dst[n][k] = *(const PG8_LAS bf16x8*)(lds + PG8_SB(b, h) + boff + n * 2048 + k * 1024); } while (0)
; #define PG8_MMA(ai, bj, At, Bt) do { __builtin_amdgcn_s_setprio(1); _Pragma("unroll") for (int m = 0; m < 4; ++m) _Pragma("unroll") for (int n = 0; n < 2; ++n) _Pragma("unroll") for (int k = 0; k < 2; ++k) \
;         acc[ai][bj][m][n] = __builtin_amdgcn_mfma_f32_16x16x32_bf16(Bt[n][k], At[m][k], acc[ai][bj][m][n], 0, 0, 0); __builtin_amdgcn_s_setprio(0); } while (0)
; #define PG8_WAIT_V(n) asm volatile("s_waitcnt vmcnt(" #n ")" ::: "memory")
; #define PG8_WAIT_L(n) asm volatile("s_waitcnt lgkmcnt(" #n ")" ::: "memory")
; #define PG8_BAR __builtin_amdgcn_s_barrier()
; #define PG8_SCHED __builtin_amdgcn_sched_barrier(0)
; template <class Epi, class Sched, bool ALIGN_EPI = false, bool SP2 = false>
; __device__ __forceinline__ void gemm_phase(PG8_LAS unsigned char* lds, const Gemm g, const Sched& S, const Epi& E) {
;     ...
;             PG8_WAIT_V(8); PG8_WAIT_L(0); PG8_BAR; PG8_MMA(0, 0, At, B0); PG8_MMA(0, 1, At, B1); PG8_BAR; PG8_SCHED;
;             PG8_LDA(At, 0, 1); PG8_STAGE(PG8_SB(0, 0), b2, voffB); PG8_STAGE(PG8_SB(0, 1), b2 + hstep, voffB); PG8_STAGE(PG8_SA(0, 0), a2, voffA);
;             PG8_WAIT_V(8); PG8_WAIT_L(0); PG8_BAR; PG8_MMA(1, 0, At, B0); PG8_MMA(1, 1, At, B1); PG8_BAR; PG8_SCHED;
;             PG8_LDB(B0, 1, 0); PG8_LDB(B1, 1, 1); PG8_SCHED; PG8_LDA(At, 1, 0); PG8_STAGE(PG8_SA(0, 1), a2 + hstep, voffA);
	s_waitcnt lgkmcnt(0)
	v_mfma_f32_16x16x32_bf16 v[190:193], v[2:5], v[34:37], v[190:193]
	v_mfma_f32_16x16x32_bf16 v[186:189], v[10:13], v[34:37], v[186:189]
	v_mfma_f32_16x16x32_bf16 v[174:177], v[2:5], v[42:45], v[174:177]
	v_mfma_f32_16x16x32_bf16 v[170:173], v[10:13], v[42:45], v[170:173]
	v_mfma_f32_16x16x32_bf16 v[158:161], v[2:5], v[50:53], v[158:161]
	v_mfma_f32_16x16x32_bf16 v[154:157], v[10:13], v[50:53], v[154:157]
	v_mfma_f32_16x16x32_bf16 v[142:145], v[2:5], v[58:61], v[142:145]
	v_mfma_f32_16x16x32_bf16 v[138:141], v[10:13], v[58:61], v[138:141]
	v_mfma_f32_16x16x32_bf16 v[190:193], v[6:9], v[38:41], v[190:193]
	v_mfma_f32_16x16x32_bf16 v[186:189], v[14:17], v[38:41], v[186:189]
	v_mfma_f32_16x16x32_bf16 v[174:177], v[6:9], v[46:49], v[174:177]
	v_mfma_f32_16x16x32_bf16 v[170:173], v[14:17], v[46:49], v[170:173]
	v_mfma_f32_16x16x32_bf16 v[158:161], v[6:9], v[54:57], v[158:161]
	v_mfma_f32_16x16x32_bf16 v[154:157], v[14:17], v[54:57], v[154:157]
	v_mfma_f32_16x16x32_bf16 v[142:145], v[6:9], v[62:65], v[142:145]
	v_mfma_f32_16x16x32_bf16 v[138:141], v[14:17], v[62:65], v[138:141]
	v_mfma_f32_16x16x32_bf16 v[182:185], v[18:21], v[34:37], v[182:185]
	v_mfma_f32_16x16x32_bf16 v[34:37], v[26:29], v[34:37], v[178:181]
	v_mfma_f32_16x16x32_bf16 v[182:185], v[22:25], v[38:41], v[182:185]
	v_mfma_f32_16x16x32_bf16 v[34:37], v[30:33], v[38:41], v[34:37]
	v_mfma_f32_16x16x32_bf16 v[38:41], v[18:21], v[42:45], v[166:169]
	v_mfma_f32_16x16x32_bf16 v[42:45], v[26:29], v[42:45], v[162:165]
	v_mfma_f32_16x16x32_bf16 v[38:41], v[22:25], v[46:49], v[38:41]
	v_mfma_f32_16x16x32_bf16 v[42:45], v[30:33], v[46:49], v[42:45]
	v_mfma_f32_16x16x32_bf16 v[46:49], v[18:21], v[50:53], v[150:153]
	v_mfma_f32_16x16x32_bf16 v[50:53], v[26:29], v[50:53], v[146:149]
	v_mfma_f32_16x16x32_bf16 v[46:49], v[22:25], v[54:57], v[46:49]
	v_mfma_f32_16x16x32_bf16 v[50:53], v[30:33], v[54:57], v[50:53]
	v_mfma_f32_16x16x32_bf16 v[54:57], v[18:21], v[58:61], v[134:137]
	v_mfma_f32_16x16x32_bf16 v[58:61], v[26:29], v[58:61], v[130:133]
	v_mfma_f32_16x16x32_bf16 v[54:57], v[22:25], v[62:65], v[54:57]
	v_mfma_f32_16x16x32_bf16 v[58:61], v[30:33], v[62:65], v[58:61]
	s_barrier
	s_add_i32 s13, s13, s41
	v_lshl_add_u64 v[228:229], s[18:19], 0, v[0:1]
	s_mov_b32 m0, s13
	ds_read_b128 v[62:65], v243 offset:16384
	ds_read_b128 v[130:133], v243 offset:17408
	ds_read_b128 v[134:137], v243 offset:18432
	ds_read_b128 v[146:149], v243 offset:19456
	ds_read_b128 v[150:153], v243 offset:20480
	ds_read_b128 v[162:165], v243 offset:21504
	ds_read_b128 v[166:169], v243 offset:22528
	ds_read_b128 v[178:181], v243 offset:23552
	global_load_lds_dwordx4 v[228:229], off
	s_add_i32 m0, s13, 0x2000
	s_add_u32 s18, s18, s58
	v_lshl_add_u64 v[230:231], v[228:229], 0, s[56:57]
	s_addc_u32 s19, s19, s59
	s_add_i32 s3, s3, s41
	global_load_lds_dwordx4 v[230:231], off
	v_lshl_add_u64 v[244:245], s[18:19], 0, v[0:1]
	s_mov_b32 m0, s3
	v_lshl_add_u64 v[246:247], v[244:245], 0, s[56:57]
	global_load_lds_dwordx4 v[244:245], off
	s_add_i32 m0, s3, 0x2000
	v_lshl_add_u64 v[248:249], s[8:9], 0, v[216:217]
	global_load_lds_dwordx4 v[246:247], off
	s_mov_b32 m0, s90
	v_lshl_add_u64 v[250:251], v[248:249], 0, s[56:57]
	global_load_lds_dwordx4 v[248:249], off
	s_mov_b32 m0, s91
	s_nop 0
	global_load_lds_dwordx4 v[250:251], off
	s_waitcnt vmcnt(8)
	s_waitcnt lgkmcnt(0)
	s_barrier
	s_waitcnt lgkmcnt(0)
	v_mfma_f32_16x16x32_bf16 v[126:129], v[2:5], v[62:65], v[126:129]
	v_mfma_f32_16x16x32_bf16 v[122:125], v[10:13], v[62:65], v[122:125]
	v_mfma_f32_16x16x32_bf16 v[110:113], v[2:5], v[134:137], v[110:113]
	v_mfma_f32_16x16x32_bf16 v[106:109], v[10:13], v[134:137], v[106:109]
	v_mfma_f32_16x16x32_bf16 v[94:97], v[2:5], v[150:153], v[94:97]
	v_mfma_f32_16x16x32_bf16 v[90:93], v[10:13], v[150:153], v[90:93]
	v_mfma_f32_16x16x32_bf16 v[2:5], v[2:5], v[166:169], v[78:81]
	v_mfma_f32_16x16x32_bf16 v[126:129], v[6:9], v[130:133], v[126:129]
	v_mfma_f32_16x16x32_bf16 v[122:125], v[14:17], v[130:133], v[122:125]
	v_mfma_f32_16x16x32_bf16 v[110:113], v[6:9], v[146:149], v[110:113]
	v_mfma_f32_16x16x32_bf16 v[106:109], v[14:17], v[146:149], v[106:109]
	v_mfma_f32_16x16x32_bf16 v[94:97], v[6:9], v[162:165], v[94:97]
	v_mfma_f32_16x16x32_bf16 v[90:93], v[14:17], v[162:165], v[90:93]
	v_mfma_f32_16x16x32_bf16 v[2:5], v[6:9], v[178:181], v[2:5]
	v_mfma_f32_16x16x32_bf16 v[6:9], v[10:13], v[166:169], v[74:77]
	v_mfma_f32_16x16x32_bf16 v[6:9], v[14:17], v[178:181], v[6:9]
	v_mfma_f32_16x16x32_bf16 v[74:77], v[26:29], v[134:137], v[98:101]
	v_mfma_f32_16x16x32_bf16 v[98:101], v[30:33], v[146:149], v[74:77]
	v_mfma_f32_16x16x32_bf16 v[74:77], v[18:21], v[150:153], v[86:89]
	v_mfma_f32_16x16x32_bf16 v[10:13], v[18:21], v[62:65], v[118:121]
	v_mfma_f32_16x16x32_bf16 v[14:17], v[26:29], v[62:65], v[114:117]
	v_mfma_f32_16x16x32_bf16 v[62:65], v[18:21], v[134:137], v[102:105]
	v_mfma_f32_16x16x32_bf16 v[86:89], v[22:25], v[162:165], v[74:77]
	v_mfma_f32_16x16x32_bf16 v[74:77], v[26:29], v[150:153], v[82:85]
	v_mfma_f32_16x16x32_bf16 v[18:21], v[18:21], v[166:169], v[70:73]
	v_mfma_f32_16x16x32_bf16 v[10:13], v[22:25], v[130:133], v[10:13]
	v_mfma_f32_16x16x32_bf16 v[62:65], v[22:25], v[146:149], v[62:65]
	v_mfma_f32_16x16x32_bf16 v[82:85], v[30:33], v[162:165], v[74:77]
	v_mfma_f32_16x16x32_bf16 v[18:21], v[22:25], v[178:181], v[18:21]
	v_mfma_f32_16x16x32_bf16 v[22:25], v[26:29], v[166:169], v[66:69]
	v_mfma_f32_16x16x32_bf16 v[14:17], v[30:33], v[130:133], v[14:17]
	v_mfma_f32_16x16x32_bf16 v[22:25], v[30:33], v[178:181], v[22:25]
	s_barrier
; #define PG8_STAGE(bufoff, gbase, voff) do { _Pragma("unroll") for (int _i = 0; _i < 2; ++_i) \
;         __builtin_amdgcn_global_load_lds((const unsigned*)((const char*)(gbase) + (size_t)_i * r64 + (voff)), (PG8_LAS unsigned*)(lds + (bufoff) + ldsw + _i * 8192), 16, 0, 0); } while (0)
; #define PG8_LDA(dst, b, h) do { _Pragma("unroll") for (int m = 0; m < 4; ++m) _Pragma("unroll") for (int k = 0; k < 2; ++k) dst[m][k] = *(const PG8_LAS bf16x8*)(lds + PG8_SA(b, h) + aoff + m * 2048 + k * 1024); } while (0)
; #define PG8_LDB(dst, b, h) do { _Pragma("unroll") for (int n = 0; n < 2; ++n) _Pragma("unroll") for (int k = 0; k < 2; ++k) dst[n][k] = *(const PG8_LAS bf16x8*)(lds + PG8_SB(b, h) + boff + n * 2048 + k * 1024); } while (0)
; #define PG8_MMA(ai, bj, At, Bt) do { __builtin_amdgcn_s_setprio(1); _Pragma("unroll") for (int m = 0; m < 4; ++m) _Pragma("unroll") for (int n = 0; n < 2; ++n) _Pragma("unroll") for (int k = 0; k < 2; ++k) \
;         acc[ai][bj][m][n] = __builtin_amdgcn_mfma_f32_16x16x32_bf16(Bt[n][k], At[m][k], acc[ai][bj][m][n], 0, 0, 0); __builtin_amdgcn_s_setprio(0); } while (0)
; #define PG8_WAIT_V(n) asm volatile("s_waitcnt vmcnt(" #n ")" ::: "memory")
; #define PG8_WAIT_L(n) asm volatile("s_waitcnt lgkmcnt(" #n ")" ::: "memory")
; #define PG8_BAR __builtin_amdgcn_s_barrier()
; #define PG8_SCHED __builtin_amdgcn_sched_barrier(0)
; template <class Epi, class Sched, bool ALIGN_EPI = false, bool SP2 = false>
; __device__ __forceinline__ void gemm_phase(PG8_LAS unsigned char* lds, const Gemm g, const Sched& S, const Epi& E) {
;     ...
;             PG8_LDB(B0, 1, 0); PG8_LDB(B1, 1, 1); PG8_SCHED; PG8_LDA(At, 1, 0); PG8_STAGE(PG8_SA(0, 1), a2 + hstep, voffA);
;             PG8_WAIT_V(8); PG8_WAIT_L(0); PG8_BAR; PG8_MMA(0, 0, At, B0); PG8_MMA(0, 1, At, B1); PG8_BAR; PG8_SCHED;
;             PG8_LDA(At, 1, 1); PG8_STAGE(PG8_SB(1, 0), b3, voffB); PG8_STAGE(PG8_SB(1, 1), b3 + hstep, voffB); PG8_STAGE(PG8_SA(1, 0), a3, voffA);
;             PG8_WAIT_V(8); PG8_WAIT_L(0); PG8_BAR; PG8_MMA(1, 0, At, B0); PG8_MMA(1, 1, At, B1); PG8_BAR; PG8_SCHED;
	s_add_i32 s3, 0, 0x18000
	s_add_i32 s13, 0, 0x1c000
	v_add_u32_e32 v70, s3, v242
	v_add_u32_e32 v74, s13, v242
	ds_read_b128 v[26:29], v70
	ds_read_b128 v[30:33], v70 offset:1024
	ds_read_b128 v[66:69], v70 offset:2048
	ds_read_b128 v[70:73], v70 offset:3072
	ds_read_b128 v[194:197], v74
	ds_read_b128 v[198:201], v74 offset:1024
	ds_read_b128 v[202:205], v74 offset:2048
	ds_read_b128 v[206:209], v74 offset:3072
	s_add_u32 s8, s8, s58
	s_addc_u32 s9, s9, s59
	s_mov_b32 m0, s36
	v_lshl_add_u64 v[134:135], s[8:9], 0, v[216:217]
	ds_read_b128 v[74:77], v243 offset:32768
	ds_read_b128 v[78:81], v243 offset:33792
	ds_read_b128 v[102:105], v243 offset:34816
	ds_read_b128 v[114:117], v243 offset:35840
	ds_read_b128 v[118:121], v243 offset:36864
	ds_read_b128 v[130:133], v243 offset:37888
	ds_read_b128 v[210:213], v243 offset:38912
	ds_read_b128 v[224:227], v243 offset:39936
	global_load_lds_dwordx4 v[134:135], off
	v_lshl_add_u64 v[134:135], v[134:135], 0, s[56:57]
	s_mov_b32 m0, s62
	s_nop 0
	global_load_lds_dwordx4 v[134:135], off
	s_waitcnt vmcnt(8)
	s_waitcnt lgkmcnt(0)
	s_barrier
	s_waitcnt lgkmcnt(0)
	v_mfma_f32_16x16x32_bf16 v[134:137], v[26:29], v[74:77], v[190:193]
	v_mfma_f32_16x16x32_bf16 v[190:193], v[30:33], v[78:81], v[134:137]
	v_mfma_f32_16x16x32_bf16 v[134:137], v[66:69], v[74:77], v[186:189]
	v_mfma_f32_16x16x32_bf16 v[186:189], v[70:73], v[78:81], v[134:137]
	v_mfma_f32_16x16x32_bf16 v[134:137], v[26:29], v[102:105], v[174:177]
	v_mfma_f32_16x16x32_bf16 v[174:177], v[30:33], v[114:117], v[134:137]
	v_mfma_f32_16x16x32_bf16 v[134:137], v[66:69], v[102:105], v[170:173]
	v_mfma_f32_16x16x32_bf16 v[170:173], v[70:73], v[114:117], v[134:137]
	v_mfma_f32_16x16x32_bf16 v[134:137], v[26:29], v[118:121], v[158:161]
	v_mfma_f32_16x16x32_bf16 v[158:161], v[30:33], v[130:133], v[134:137]
	v_mfma_f32_16x16x32_bf16 v[134:137], v[66:69], v[118:121], v[154:157]
	v_mfma_f32_16x16x32_bf16 v[154:157], v[70:73], v[130:133], v[134:137]
	v_mfma_f32_16x16x32_bf16 v[134:137], v[26:29], v[210:213], v[142:145]
	v_mfma_f32_16x16x32_bf16 v[142:145], v[30:33], v[224:227], v[134:137]
	v_mfma_f32_16x16x32_bf16 v[134:137], v[66:69], v[210:213], v[138:141]
	v_mfma_f32_16x16x32_bf16 v[138:141], v[70:73], v[224:227], v[134:137]
	v_mfma_f32_16x16x32_bf16 v[34:37], v[202:205], v[74:77], v[34:37]
	v_mfma_f32_16x16x32_bf16 v[178:181], v[206:209], v[78:81], v[34:37]
	v_mfma_f32_16x16x32_bf16 v[34:37], v[194:197], v[102:105], v[38:41]
	v_mfma_f32_16x16x32_bf16 v[166:169], v[198:201], v[114:117], v[34:37]
	v_mfma_f32_16x16x32_bf16 v[34:37], v[202:205], v[102:105], v[42:45]
	v_mfma_f32_16x16x32_bf16 v[162:165], v[206:209], v[114:117], v[34:37]
	v_mfma_f32_16x16x32_bf16 v[34:37], v[194:197], v[118:121], v[46:49]
	v_mfma_f32_16x16x32_bf16 v[150:153], v[198:201], v[130:133], v[34:37]
	v_mfma_f32_16x16x32_bf16 v[34:37], v[202:205], v[118:121], v[50:53]
	v_mfma_f32_16x16x32_bf16 v[134:137], v[194:197], v[74:77], v[182:185]
	v_mfma_f32_16x16x32_bf16 v[146:149], v[206:209], v[130:133], v[34:37]
	v_mfma_f32_16x16x32_bf16 v[34:37], v[194:197], v[210:213], v[54:57]
	v_mfma_f32_16x16x32_bf16 v[182:185], v[198:201], v[78:81], v[134:137]
	v_mfma_f32_16x16x32_bf16 v[134:137], v[198:201], v[224:227], v[34:37]
	v_mfma_f32_16x16x32_bf16 v[34:37], v[202:205], v[210:213], v[58:61]
	v_mfma_f32_16x16x32_bf16 v[130:133], v[206:209], v[224:227], v[34:37]
	s_barrier
	s_add_i32 s3, s3, s41
	v_lshl_add_u64 v[74:75], v[228:229], 0, s[34:35]
	s_mov_b32 m0, s3
	s_nop 1
	ds_read_b128 v[34:37], v243 offset:49152
	ds_read_b128 v[38:41], v243 offset:50176
	ds_read_b128 v[42:45], v243 offset:51200
	ds_read_b128 v[46:49], v243 offset:52224
	ds_read_b128 v[50:53], v243 offset:53248
	ds_read_b128 v[54:57], v243 offset:54272
	ds_read_b128 v[58:61], v243 offset:55296
	ds_read_b128 v[210:213], v243 offset:56320
	global_load_lds_dwordx4 v[74:75], off
	v_lshl_add_u64 v[74:75], v[230:231], 0, s[34:35]
	s_add_i32 m0, s3, 0x2000
	s_add_i32 s3, s13, s41
	global_load_lds_dwordx4 v[74:75], off
	v_lshl_add_u64 v[74:75], v[244:245], 0, s[34:35]
	s_mov_b32 m0, s3
	s_nop 0
	global_load_lds_dwordx4 v[74:75], off
	v_lshl_add_u64 v[74:75], v[246:247], 0, s[34:35]
	s_add_i32 m0, s3, 0x2000
	s_nop 0
	global_load_lds_dwordx4 v[74:75], off
	v_lshl_add_u64 v[74:75], v[248:249], 0, s[34:35]
	s_mov_b32 m0, s81
	s_nop 0
	global_load_lds_dwordx4 v[74:75], off
	v_lshl_add_u64 v[74:75], v[250:251], 0, s[34:35]
	s_mov_b32 m0, s1
	s_nop 0
	global_load_lds_dwordx4 v[74:75], off
	s_waitcnt vmcnt(8)
	s_waitcnt lgkmcnt(0)
	s_barrier
	s_waitcnt lgkmcnt(0)
	v_mfma_f32_16x16x32_bf16 v[74:77], v[26:29], v[34:37], v[126:129]
	v_mfma_f32_16x16x32_bf16 v[126:129], v[30:33], v[38:41], v[74:77]
	v_mfma_f32_16x16x32_bf16 v[74:77], v[66:69], v[34:37], v[122:125]
	v_mfma_f32_16x16x32_bf16 v[122:125], v[70:73], v[38:41], v[74:77]
	v_mfma_f32_16x16x32_bf16 v[74:77], v[26:29], v[42:45], v[110:113]
	v_mfma_f32_16x16x32_bf16 v[110:113], v[30:33], v[46:49], v[74:77]
	v_mfma_f32_16x16x32_bf16 v[74:77], v[66:69], v[42:45], v[106:109]
	v_mfma_f32_16x16x32_bf16 v[106:109], v[70:73], v[46:49], v[74:77]
	v_mfma_f32_16x16x32_bf16 v[74:77], v[26:29], v[50:53], v[94:97]
	v_mfma_f32_16x16x32_bf16 v[2:5], v[26:29], v[58:61], v[2:5]
	v_mfma_f32_16x16x32_bf16 v[94:97], v[30:33], v[54:57], v[74:77]
	v_mfma_f32_16x16x32_bf16 v[74:77], v[66:69], v[50:53], v[90:93]
	v_mfma_f32_16x16x32_bf16 v[78:81], v[30:33], v[210:213], v[2:5]
	v_mfma_f32_16x16x32_bf16 v[2:5], v[66:69], v[58:61], v[6:9]
	v_mfma_f32_16x16x32_bf16 v[90:93], v[70:73], v[54:57], v[74:77]
	v_mfma_f32_16x16x32_bf16 v[74:77], v[70:73], v[210:213], v[2:5]
	v_mfma_f32_16x16x32_bf16 v[2:5], v[194:197], v[34:37], v[10:13]
	v_mfma_f32_16x16x32_bf16 v[118:121], v[198:201], v[38:41], v[2:5]
	v_mfma_f32_16x16x32_bf16 v[2:5], v[202:205], v[34:37], v[14:17]
	v_mfma_f32_16x16x32_bf16 v[114:117], v[206:209], v[38:41], v[2:5]
	v_mfma_f32_16x16x32_bf16 v[2:5], v[194:197], v[42:45], v[62:65]
	v_mfma_f32_16x16x32_bf16 v[102:105], v[198:201], v[46:49], v[2:5]
	v_mfma_f32_16x16x32_bf16 v[2:5], v[202:205], v[42:45], v[98:101]
	v_mfma_f32_16x16x32_bf16 v[98:101], v[206:209], v[46:49], v[2:5]
	v_mfma_f32_16x16x32_bf16 v[2:5], v[194:197], v[50:53], v[86:89]
	v_mfma_f32_16x16x32_bf16 v[86:89], v[198:201], v[54:57], v[2:5]
	v_mfma_f32_16x16x32_bf16 v[2:5], v[202:205], v[50:53], v[82:85]
	v_mfma_f32_16x16x32_bf16 v[82:85], v[206:209], v[54:57], v[2:5]
	v_mfma_f32_16x16x32_bf16 v[2:5], v[194:197], v[58:61], v[18:21]
	v_mfma_f32_16x16x32_bf16 v[70:73], v[198:201], v[210:213], v[2:5]
	v_mfma_f32_16x16x32_bf16 v[2:5], v[202:205], v[58:61], v[22:25]
	v_mfma_f32_16x16x32_bf16 v[66:69], v[206:209], v[210:213], v[2:5]
	s_barrier
	s_add_u32 s6, s6, 0x100
	s_addc_u32 s7, s7, 0
	s_add_u32 s10, s10, 0x100
	s_addc_u32 s11, s11, 0
	s_cmp_ge_u32 s12, s2
	s_mov_b32 s8, s12
	s_cbranch_scc0 .LBB0_168
